# P5 K-loop: LDS-DMA staging issued in the first gaps of the MFMA block instead of the load segment (waits kept, counts adjusted)
# baseline (speedup 1.0000x reference)
.LBB0_1134:
	s_ashr_i32 s57, s56, 31
	s_lshl_b64 s[60:61], s[56:57], 19
	s_add_u32 s60, s42, s60
	s_addc_u32 s61, s43, s61
	s_and_b64 s[62:63], s[10:11], exec
	s_cselect_b32 s57, s61, s27
	s_cselect_b32 s79, s60, s26
	s_ashr_i32 s59, s58, 31
	s_lshl_b64 s[62:63], s[58:59], 19
	v_readlane_b32 s70, v254, 7
	v_readlane_b32 s71, v254, 8
	s_add_u32 s62, s70, s62
	s_addc_u32 s63, s71, s63
	s_and_b64 s[70:71], s[10:11], exec
	s_cselect_b32 s59, s63, s69
	s_cselect_b32 s80, s62, s68
	s_add_u32 s81, s68, 0x100
	v_lshl_add_u64 v[138:139], s[26:27], 0, v[132:133]
	s_addc_u32 s82, s69, 0
	s_mov_b32 s83, -2
	s_mov_b64 s[68:69], 0
	ds_read_b128 v[168:171], v145
	ds_read_b128 v[174:177], v146
	ds_read_b128 v[178:181], v147
	ds_read_b128 v[182:185], v148
	ds_read_b128 v[194:197], v149
	ds_read_b128 v[198:201], v150
	ds_read_b128 v[202:205], v151
	ds_read_b128 v[206:209], v152
	ds_read_b128 v[210:213], v153
	ds_read_b128 v[214:217], v153 offset:2048
	ds_read_b128 v[218:221], v154
	ds_read_b128 v[222:225], v154 offset:2048
	ds_read_b128 v[226:229], v153 offset:4096
	ds_read_b128 v[230:233], v153 offset:6144
	ds_read_b128 v[234:237], v154 offset:4096
	ds_read_b128 v[238:241], v154 offset:6144
	s_waitcnt lgkmcnt(0)
	s_barrier
	v_mfma_f32_16x16x32_bf16 v[128:131], v[168:171], v[210:213], 0
	s_add_u32 s70, s26, s68
	s_addc_u32 s71, s27, s69
	v_mfma_f32_16x16x32_bf16 v[124:127], v[178:181], v[210:213], 0
	s_add_u32 s70, s70, 0x100
	s_addc_u32 s71, s71, 0
	v_mfma_f32_16x16x32_bf16 v[112:115], v[168:171], v[214:217], 0
	s_add_u32 s84, s81, s68
	s_addc_u32 s85, s82, s69
	v_mfma_f32_16x16x32_bf16 v[108:111], v[178:181], v[214:217], 0
	s_cmpk_eq_i32 s68, 0x700
	s_cselect_b32 s85, s59, s85
	v_mfma_f32_16x16x32_bf16 v[96:99], v[168:171], v[226:229], 0
	s_cselect_b32 s84, s80, s84
	s_cselect_b32 s71, s57, s71
	v_mfma_f32_16x16x32_bf16 v[92:95], v[178:181], v[226:229], 0
	s_cselect_b32 s70, s79, s70
	v_lshl_add_u64 v[140:141], v[138:139], 0, s[68:69]
	v_mfma_f32_16x16x32_bf16 v[80:83], v[168:171], v[230:233], 0
	v_lshl_add_u64 v[242:243], v[140:141], 0, s[22:23]
	s_add_i32 m0, s34, 0x8000
	v_mfma_f32_16x16x32_bf16 v[76:79], v[178:181], v[230:233], 0
	s_mov_b64 s[86:87], 0x20080
	global_load_lds_dwordx4 v[242:243], off
	v_mfma_f32_16x16x32_bf16 v[128:131], v[174:177], v[218:221], v[128:131]
	v_lshl_add_u64 v[242:243], v[140:141], 0, s[86:87]
	s_add_i32 m0, s34, 0xa000
	v_mfma_f32_16x16x32_bf16 v[124:127], v[182:185], v[218:221], v[124:127]
	s_mov_b64 s[86:87], 0x60080
	global_load_lds_dwordx4 v[242:243], off
	v_mfma_f32_16x16x32_bf16 v[112:115], v[174:177], v[222:225], v[112:115]
	v_lshl_add_u64 v[242:243], v[140:141], 0, s[24:25]
	s_add_i32 m0, s34, 0xc000
	v_mfma_f32_16x16x32_bf16 v[108:111], v[182:185], v[222:225], v[108:111]
	v_lshl_add_u64 v[140:141], v[140:141], 0, s[86:87]
	global_load_lds_dwordx4 v[242:243], off
	v_mfma_f32_16x16x32_bf16 v[96:99], v[174:177], v[234:237], v[96:99]
	s_add_i32 m0, s34, 0xe000
	s_nop 0
	v_mfma_f32_16x16x32_bf16 v[92:95], v[182:185], v[234:237], v[92:95]
	global_load_lds_dwordx4 v[140:141], off
	v_mfma_f32_16x16x32_bf16 v[80:83], v[174:177], v[238:241], v[80:83]
	v_mfma_f32_16x16x32_bf16 v[76:79], v[182:185], v[238:241], v[76:79]
	v_mfma_f32_16x16x32_bf16 v[120:123], v[194:197], v[210:213], 0
	v_mfma_f32_16x16x32_bf16 v[116:119], v[202:205], v[210:213], 0
	v_mfma_f32_16x16x32_bf16 v[104:107], v[194:197], v[214:217], 0
	v_mfma_f32_16x16x32_bf16 v[100:103], v[202:205], v[214:217], 0
	v_mfma_f32_16x16x32_bf16 v[88:91], v[194:197], v[226:229], 0
	v_mfma_f32_16x16x32_bf16 v[84:87], v[202:205], v[226:229], 0
	v_mfma_f32_16x16x32_bf16 v[72:75], v[194:197], v[230:233], 0
	v_mfma_f32_16x16x32_bf16 v[68:71], v[202:205], v[230:233], 0
	v_mfma_f32_16x16x32_bf16 v[120:123], v[198:201], v[218:221], v[120:123]
	v_mfma_f32_16x16x32_bf16 v[116:119], v[206:209], v[218:221], v[116:119]
	v_mfma_f32_16x16x32_bf16 v[104:107], v[198:201], v[222:225], v[104:107]
	v_mfma_f32_16x16x32_bf16 v[100:103], v[206:209], v[222:225], v[100:103]
	v_mfma_f32_16x16x32_bf16 v[88:91], v[198:201], v[234:237], v[88:91]
	v_mfma_f32_16x16x32_bf16 v[84:87], v[206:209], v[234:237], v[84:87]
	v_mfma_f32_16x16x32_bf16 v[72:75], v[198:201], v[238:241], v[72:75]
	v_mfma_f32_16x16x32_bf16 v[68:71], v[206:209], v[238:241], v[68:71]
	s_barrier
	ds_read_b128 v[210:213], v153 offset:16384
	ds_read_b128 v[214:217], v153 offset:18432
	ds_read_b128 v[218:221], v154 offset:16384
	ds_read_b128 v[222:225], v154 offset:18432
	ds_read_b128 v[226:229], v153 offset:20480
	ds_read_b128 v[230:233], v153 offset:22528
	ds_read_b128 v[234:237], v154 offset:20480
	ds_read_b128 v[238:241], v154 offset:22528
	s_waitcnt vmcnt(0)
	s_waitcnt lgkmcnt(0)
	s_barrier
	v_mfma_f32_16x16x32_bf16 v[64:67], v[168:171], v[210:213], 0
	v_lshl_add_u64 v[140:141], s[84:85], 0, v[158:159]
	s_add_i32 s84, s67, s3
	v_mfma_f32_16x16x32_bf16 v[60:63], v[178:181], v[210:213], 0
	s_mov_b32 m0, s84
	global_load_lds_dwordx4 v[140:141], off
	v_mfma_f32_16x16x32_bf16 v[48:51], v[168:171], v[214:217], 0
	v_lshl_add_u64 v[242:243], v[140:141], 0, s[0:1]
	s_add_i32 m0, s84, 0x2000
	v_mfma_f32_16x16x32_bf16 v[44:47], v[178:181], v[214:217], 0
	s_add_i32 s84, s72, s3
	global_load_lds_dwordx4 v[242:243], off
	v_mfma_f32_16x16x32_bf16 v[32:35], v[168:171], v[226:229], 0
	v_lshl_add_u64 v[242:243], v[140:141], 0, s[12:13]
	s_mov_b32 m0, s84
	v_mfma_f32_16x16x32_bf16 v[28:31], v[178:181], v[226:229], 0
	s_nop 0
	global_load_lds_dwordx4 v[242:243], off
	v_mfma_f32_16x16x32_bf16 v[16:19], v[168:171], v[230:233], 0
	v_lshl_add_u64 v[242:243], v[140:141], 0, s[14:15]
	s_add_i32 m0, s84, 0x2000
	v_mfma_f32_16x16x32_bf16 v[12:15], v[178:181], v[230:233], 0
	s_nop 0
	global_load_lds_dwordx4 v[242:243], off
	v_mfma_f32_16x16x32_bf16 v[64:67], v[174:177], v[218:221], v[64:67]
	v_mfma_f32_16x16x32_bf16 v[60:63], v[182:185], v[218:221], v[60:63]
	v_mfma_f32_16x16x32_bf16 v[48:51], v[174:177], v[222:225], v[48:51]
	v_mfma_f32_16x16x32_bf16 v[44:47], v[182:185], v[222:225], v[44:47]
	v_mfma_f32_16x16x32_bf16 v[32:35], v[174:177], v[234:237], v[32:35]
	v_mfma_f32_16x16x32_bf16 v[28:31], v[182:185], v[234:237], v[28:31]
	v_mfma_f32_16x16x32_bf16 v[16:19], v[174:177], v[238:241], v[16:19]
	v_mfma_f32_16x16x32_bf16 v[12:15], v[182:185], v[238:241], v[12:15]
	v_mfma_f32_16x16x32_bf16 v[56:59], v[194:197], v[210:213], 0
	v_mfma_f32_16x16x32_bf16 v[52:55], v[202:205], v[210:213], 0
	v_mfma_f32_16x16x32_bf16 v[40:43], v[194:197], v[214:217], 0
	v_mfma_f32_16x16x32_bf16 v[36:39], v[202:205], v[214:217], 0
	v_mfma_f32_16x16x32_bf16 v[24:27], v[194:197], v[226:229], 0
	v_mfma_f32_16x16x32_bf16 v[20:23], v[202:205], v[226:229], 0
	v_mfma_f32_16x16x32_bf16 v[8:11], v[194:197], v[230:233], 0
	v_mfma_f32_16x16x32_bf16 v[4:7], v[202:205], v[230:233], 0
	v_mfma_f32_16x16x32_bf16 v[56:59], v[198:201], v[218:221], v[56:59]
	v_mfma_f32_16x16x32_bf16 v[52:55], v[206:209], v[218:221], v[52:55]
	v_mfma_f32_16x16x32_bf16 v[40:43], v[198:201], v[222:225], v[40:43]
	v_mfma_f32_16x16x32_bf16 v[36:39], v[206:209], v[222:225], v[36:39]
	v_mfma_f32_16x16x32_bf16 v[24:27], v[198:201], v[234:237], v[24:27]
	v_mfma_f32_16x16x32_bf16 v[20:23], v[206:209], v[234:237], v[20:23]
	v_mfma_f32_16x16x32_bf16 v[8:11], v[198:201], v[238:241], v[8:11]
	v_mfma_f32_16x16x32_bf16 v[4:7], v[206:209], v[238:241], v[4:7]
	s_barrier
	ds_read_b128 v[168:171], v163
	ds_read_b128 v[174:177], v164
	ds_read_b128 v[178:181], v155
	ds_read_b128 v[182:185], v160
	ds_read_b128 v[194:197], v165
	ds_read_b128 v[198:201], v166
	ds_read_b128 v[202:205], v161
	ds_read_b128 v[206:209], v162
	ds_read_b128 v[210:213], v153 offset:32768
	ds_read_b128 v[214:217], v153 offset:34816
	ds_read_b128 v[218:221], v154 offset:32768
	ds_read_b128 v[222:225], v154 offset:34816
	ds_read_b128 v[226:229], v153 offset:36864
	ds_read_b128 v[230:233], v153 offset:38912
	ds_read_b128 v[234:237], v154 offset:36864
	ds_read_b128 v[238:241], v154 offset:38912
	s_waitcnt vmcnt(4)
	s_waitcnt lgkmcnt(0)
	s_barrier
	v_mfma_f32_16x16x32_bf16 v[128:131], v[168:171], v[210:213], v[128:131]
	s_mov_b32 m0, s34
	v_lshl_add_u64 v[242:243], s[70:71], 0, v[0:1]
	v_mfma_f32_16x16x32_bf16 v[124:127], v[178:181], v[210:213], v[124:127]
	global_load_lds_dwordx4 v[242:243], off
	v_lshl_add_u64 v[244:245], v[242:243], 0, s[16:17]
	v_mfma_f32_16x16x32_bf16 v[112:115], v[168:171], v[214:217], v[112:115]
	s_mov_b32 m0, s35
	s_nop 0
	v_mfma_f32_16x16x32_bf16 v[108:111], v[178:181], v[214:217], v[108:111]
	global_load_lds_dwordx4 v[244:245], off
	v_lshl_add_u64 v[244:245], v[242:243], 0, s[0:1]
	v_mfma_f32_16x16x32_bf16 v[96:99], v[168:171], v[226:229], v[96:99]
	s_mov_b32 m0, s38
	v_lshl_add_u64 v[242:243], v[242:243], 0, s[18:19]
	v_mfma_f32_16x16x32_bf16 v[92:95], v[178:181], v[226:229], v[92:95]
	global_load_lds_dwordx4 v[244:245], off
	s_mov_b32 m0, s39
	v_mfma_f32_16x16x32_bf16 v[80:83], v[168:171], v[230:233], v[80:83]
	s_nop 0
	global_load_lds_dwordx4 v[242:243], off
	v_mfma_f32_16x16x32_bf16 v[76:79], v[178:181], v[230:233], v[76:79]
	v_mfma_f32_16x16x32_bf16 v[128:131], v[174:177], v[218:221], v[128:131]
	v_mfma_f32_16x16x32_bf16 v[124:127], v[182:185], v[218:221], v[124:127]
	v_mfma_f32_16x16x32_bf16 v[112:115], v[174:177], v[222:225], v[112:115]
	v_mfma_f32_16x16x32_bf16 v[108:111], v[182:185], v[222:225], v[108:111]
	v_mfma_f32_16x16x32_bf16 v[96:99], v[174:177], v[234:237], v[96:99]
	v_mfma_f32_16x16x32_bf16 v[92:95], v[182:185], v[234:237], v[92:95]
	v_mfma_f32_16x16x32_bf16 v[80:83], v[174:177], v[238:241], v[80:83]
	v_mfma_f32_16x16x32_bf16 v[76:79], v[182:185], v[238:241], v[76:79]
	v_mfma_f32_16x16x32_bf16 v[120:123], v[194:197], v[210:213], v[120:123]
	v_mfma_f32_16x16x32_bf16 v[116:119], v[202:205], v[210:213], v[116:119]
	v_mfma_f32_16x16x32_bf16 v[104:107], v[194:197], v[214:217], v[104:107]
	v_mfma_f32_16x16x32_bf16 v[100:103], v[202:205], v[214:217], v[100:103]
	v_mfma_f32_16x16x32_bf16 v[88:91], v[194:197], v[226:229], v[88:91]
	v_mfma_f32_16x16x32_bf16 v[84:87], v[202:205], v[226:229], v[84:87]
	v_mfma_f32_16x16x32_bf16 v[72:75], v[194:197], v[230:233], v[72:75]
	v_mfma_f32_16x16x32_bf16 v[68:71], v[202:205], v[230:233], v[68:71]
	v_mfma_f32_16x16x32_bf16 v[120:123], v[198:201], v[218:221], v[120:123]
	v_mfma_f32_16x16x32_bf16 v[116:119], v[206:209], v[218:221], v[116:119]
	v_mfma_f32_16x16x32_bf16 v[104:107], v[198:201], v[222:225], v[104:107]
	v_mfma_f32_16x16x32_bf16 v[100:103], v[206:209], v[222:225], v[100:103]
	v_mfma_f32_16x16x32_bf16 v[88:91], v[198:201], v[234:237], v[88:91]
	v_mfma_f32_16x16x32_bf16 v[84:87], v[206:209], v[234:237], v[84:87]
	v_mfma_f32_16x16x32_bf16 v[72:75], v[198:201], v[238:241], v[72:75]
	v_mfma_f32_16x16x32_bf16 v[68:71], v[206:209], v[238:241], v[68:71]
	s_barrier
	ds_read_b128 v[210:213], v153 offset:49152
	ds_read_b128 v[214:217], v153 offset:51200
	ds_read_b128 v[218:221], v154 offset:49152
	ds_read_b128 v[222:225], v154 offset:51200
	ds_read_b128 v[226:229], v153 offset:53248
	ds_read_b128 v[230:233], v153 offset:55296
	ds_read_b128 v[234:237], v154 offset:53248
	ds_read_b128 v[238:241], v154 offset:55296
	s_waitcnt vmcnt(0)
	s_waitcnt lgkmcnt(0)
	s_barrier
	v_mfma_f32_16x16x32_bf16 v[64:67], v[168:171], v[210:213], v[64:67]
	s_add_i32 s70, s73, s3
	v_lshl_add_u64 v[242:243], v[140:141], 0, s[22:23]
	v_mfma_f32_16x16x32_bf16 v[60:63], v[178:181], v[210:213], v[60:63]
	s_mov_b32 m0, s70
	global_load_lds_dwordx4 v[242:243], off
	v_mfma_f32_16x16x32_bf16 v[48:51], v[168:171], v[214:217], v[48:51]
	v_lshl_add_u64 v[242:243], v[140:141], 0, s[24:25]
	s_add_i32 m0, s70, 0x2000
	v_mfma_f32_16x16x32_bf16 v[44:47], v[178:181], v[214:217], v[44:47]
	s_add_i32 s70, s77, s3
	global_load_lds_dwordx4 v[242:243], off
	v_mfma_f32_16x16x32_bf16 v[32:35], v[168:171], v[226:229], v[32:35]
	v_lshl_add_u64 v[242:243], v[140:141], 0, s[28:29]
	s_mov_b32 m0, s70
	v_mfma_f32_16x16x32_bf16 v[28:31], v[178:181], v[226:229], v[28:31]
	v_lshl_add_u64 v[140:141], v[140:141], 0, s[36:37]
	global_load_lds_dwordx4 v[242:243], off
	v_mfma_f32_16x16x32_bf16 v[16:19], v[168:171], v[230:233], v[16:19]
	s_add_i32 m0, s70, 0x2000
	s_nop 0
	v_mfma_f32_16x16x32_bf16 v[12:15], v[178:181], v[230:233], v[12:15]
	global_load_lds_dwordx4 v[140:141], off
	v_mfma_f32_16x16x32_bf16 v[64:67], v[174:177], v[218:221], v[64:67]
	v_mfma_f32_16x16x32_bf16 v[60:63], v[182:185], v[218:221], v[60:63]
	v_mfma_f32_16x16x32_bf16 v[48:51], v[174:177], v[222:225], v[48:51]
	v_mfma_f32_16x16x32_bf16 v[44:47], v[182:185], v[222:225], v[44:47]
	v_mfma_f32_16x16x32_bf16 v[32:35], v[174:177], v[234:237], v[32:35]
	v_mfma_f32_16x16x32_bf16 v[28:31], v[182:185], v[234:237], v[28:31]
	v_mfma_f32_16x16x32_bf16 v[16:19], v[174:177], v[238:241], v[16:19]
	v_mfma_f32_16x16x32_bf16 v[12:15], v[182:185], v[238:241], v[12:15]
	v_mfma_f32_16x16x32_bf16 v[56:59], v[194:197], v[210:213], v[56:59]
	v_mfma_f32_16x16x32_bf16 v[52:55], v[202:205], v[210:213], v[52:55]
	v_mfma_f32_16x16x32_bf16 v[40:43], v[194:197], v[214:217], v[40:43]
	v_mfma_f32_16x16x32_bf16 v[36:39], v[202:205], v[214:217], v[36:39]
	v_mfma_f32_16x16x32_bf16 v[24:27], v[194:197], v[226:229], v[24:27]
	v_mfma_f32_16x16x32_bf16 v[20:23], v[202:205], v[226:229], v[20:23]
	v_mfma_f32_16x16x32_bf16 v[8:11], v[194:197], v[230:233], v[8:11]
	v_mfma_f32_16x16x32_bf16 v[4:7], v[202:205], v[230:233], v[4:7]
	v_mfma_f32_16x16x32_bf16 v[56:59], v[198:201], v[218:221], v[56:59]
	v_mfma_f32_16x16x32_bf16 v[52:55], v[206:209], v[218:221], v[52:55]
	v_mfma_f32_16x16x32_bf16 v[40:43], v[198:201], v[222:225], v[40:43]
	v_mfma_f32_16x16x32_bf16 v[36:39], v[206:209], v[222:225], v[36:39]
	v_mfma_f32_16x16x32_bf16 v[24:27], v[198:201], v[234:237], v[24:27]
	v_mfma_f32_16x16x32_bf16 v[20:23], v[206:209], v[234:237], v[20:23]
	v_mfma_f32_16x16x32_bf16 v[8:11], v[198:201], v[238:241], v[8:11]
	v_mfma_f32_16x16x32_bf16 v[4:7], v[206:209], v[238:241], v[4:7]
	s_barrier
	s_add_i32 s83, s83, 2
	s_add_u32 s68, s68, 0x100
	s_addc_u32 s69, s69, 0
	s_cmp_gt_u32 s83, 13
.LBB0_1135:
	ds_read_b128 v[168:171], v145
	ds_read_b128 v[174:177], v146
	ds_read_b128 v[178:181], v147
	ds_read_b128 v[182:185], v148
	ds_read_b128 v[194:197], v149
	ds_read_b128 v[198:201], v150
	ds_read_b128 v[202:205], v151
	ds_read_b128 v[206:209], v152
	ds_read_b128 v[210:213], v153
	ds_read_b128 v[214:217], v153 offset:2048
	ds_read_b128 v[218:221], v154
	ds_read_b128 v[222:225], v154 offset:2048
	ds_read_b128 v[226:229], v153 offset:4096
	ds_read_b128 v[230:233], v153 offset:6144
	ds_read_b128 v[234:237], v154 offset:4096
	ds_read_b128 v[238:241], v154 offset:6144
	s_waitcnt vmcnt(4)
	s_waitcnt lgkmcnt(0)
	s_barrier
	v_mfma_f32_16x16x32_bf16 v[128:131], v[168:171], v[210:213], v[128:131]
	s_add_u32 s70, s26, s68
	s_addc_u32 s71, s27, s69
	v_mfma_f32_16x16x32_bf16 v[124:127], v[178:181], v[210:213], v[124:127]
	s_add_u32 s70, s70, 0x100
	s_addc_u32 s71, s71, 0
	v_mfma_f32_16x16x32_bf16 v[112:115], v[168:171], v[214:217], v[112:115]
	s_add_u32 s84, s81, s68
	s_addc_u32 s85, s82, s69
	v_mfma_f32_16x16x32_bf16 v[108:111], v[178:181], v[214:217], v[108:111]
	s_cmpk_eq_i32 s68, 0x700
	s_cselect_b32 s85, s59, s85
	v_mfma_f32_16x16x32_bf16 v[96:99], v[168:171], v[226:229], v[96:99]
	s_cselect_b32 s84, s80, s84
	s_cselect_b32 s71, s57, s71
	v_mfma_f32_16x16x32_bf16 v[92:95], v[178:181], v[226:229], v[92:95]
	s_cselect_b32 s70, s79, s70
	v_lshl_add_u64 v[140:141], v[138:139], 0, s[68:69]
	v_mfma_f32_16x16x32_bf16 v[80:83], v[168:171], v[230:233], v[80:83]
	v_lshl_add_u64 v[242:243], v[140:141], 0, s[22:23]
	s_add_i32 m0, s34, 0x8000
	v_mfma_f32_16x16x32_bf16 v[76:79], v[178:181], v[230:233], v[76:79]
	s_mov_b64 s[86:87], 0x20080
	global_load_lds_dwordx4 v[242:243], off
	v_mfma_f32_16x16x32_bf16 v[128:131], v[174:177], v[218:221], v[128:131]
	v_lshl_add_u64 v[242:243], v[140:141], 0, s[86:87]
	s_add_i32 m0, s34, 0xa000
	v_mfma_f32_16x16x32_bf16 v[124:127], v[182:185], v[218:221], v[124:127]
	s_mov_b64 s[86:87], 0x60080
	global_load_lds_dwordx4 v[242:243], off
	v_mfma_f32_16x16x32_bf16 v[112:115], v[174:177], v[222:225], v[112:115]
	v_lshl_add_u64 v[242:243], v[140:141], 0, s[24:25]
	s_add_i32 m0, s34, 0xc000
	v_mfma_f32_16x16x32_bf16 v[108:111], v[182:185], v[222:225], v[108:111]
	v_lshl_add_u64 v[140:141], v[140:141], 0, s[86:87]
	global_load_lds_dwordx4 v[242:243], off
	v_mfma_f32_16x16x32_bf16 v[96:99], v[174:177], v[234:237], v[96:99]
	s_add_i32 m0, s34, 0xe000
	s_nop 0
	v_mfma_f32_16x16x32_bf16 v[92:95], v[182:185], v[234:237], v[92:95]
	global_load_lds_dwordx4 v[140:141], off
	v_mfma_f32_16x16x32_bf16 v[80:83], v[174:177], v[238:241], v[80:83]
	v_mfma_f32_16x16x32_bf16 v[76:79], v[182:185], v[238:241], v[76:79]
	v_mfma_f32_16x16x32_bf16 v[120:123], v[194:197], v[210:213], v[120:123]
	v_mfma_f32_16x16x32_bf16 v[116:119], v[202:205], v[210:213], v[116:119]
	v_mfma_f32_16x16x32_bf16 v[104:107], v[194:197], v[214:217], v[104:107]
	v_mfma_f32_16x16x32_bf16 v[100:103], v[202:205], v[214:217], v[100:103]
	v_mfma_f32_16x16x32_bf16 v[88:91], v[194:197], v[226:229], v[88:91]
	v_mfma_f32_16x16x32_bf16 v[84:87], v[202:205], v[226:229], v[84:87]
	v_mfma_f32_16x16x32_bf16 v[72:75], v[194:197], v[230:233], v[72:75]
	v_mfma_f32_16x16x32_bf16 v[68:71], v[202:205], v[230:233], v[68:71]
	v_mfma_f32_16x16x32_bf16 v[120:123], v[198:201], v[218:221], v[120:123]
	v_mfma_f32_16x16x32_bf16 v[116:119], v[206:209], v[218:221], v[116:119]
	v_mfma_f32_16x16x32_bf16 v[104:107], v[198:201], v[222:225], v[104:107]
	v_mfma_f32_16x16x32_bf16 v[100:103], v[206:209], v[222:225], v[100:103]
	v_mfma_f32_16x16x32_bf16 v[88:91], v[198:201], v[234:237], v[88:91]
	v_mfma_f32_16x16x32_bf16 v[84:87], v[206:209], v[234:237], v[84:87]
	v_mfma_f32_16x16x32_bf16 v[72:75], v[198:201], v[238:241], v[72:75]
	v_mfma_f32_16x16x32_bf16 v[68:71], v[206:209], v[238:241], v[68:71]
	s_barrier
	ds_read_b128 v[210:213], v153 offset:16384
	ds_read_b128 v[214:217], v153 offset:18432
	ds_read_b128 v[218:221], v154 offset:16384
	ds_read_b128 v[222:225], v154 offset:18432
	ds_read_b128 v[226:229], v153 offset:20480
	ds_read_b128 v[230:233], v153 offset:22528
	ds_read_b128 v[234:237], v154 offset:20480
	ds_read_b128 v[238:241], v154 offset:22528
	s_waitcnt vmcnt(0)
	s_waitcnt lgkmcnt(0)
	s_barrier
	v_mfma_f32_16x16x32_bf16 v[64:67], v[168:171], v[210:213], v[64:67]
	v_lshl_add_u64 v[140:141], s[84:85], 0, v[158:159]
	s_add_i32 s84, s67, s3
	v_mfma_f32_16x16x32_bf16 v[60:63], v[178:181], v[210:213], v[60:63]
	s_mov_b32 m0, s84
	global_load_lds_dwordx4 v[140:141], off
	v_mfma_f32_16x16x32_bf16 v[48:51], v[168:171], v[214:217], v[48:51]
	v_lshl_add_u64 v[242:243], v[140:141], 0, s[0:1]
	s_add_i32 m0, s84, 0x2000
	v_mfma_f32_16x16x32_bf16 v[44:47], v[178:181], v[214:217], v[44:47]
	s_add_i32 s84, s72, s3
	global_load_lds_dwordx4 v[242:243], off
	v_mfma_f32_16x16x32_bf16 v[32:35], v[168:171], v[226:229], v[32:35]
	v_lshl_add_u64 v[242:243], v[140:141], 0, s[12:13]
	s_mov_b32 m0, s84
	v_mfma_f32_16x16x32_bf16 v[28:31], v[178:181], v[226:229], v[28:31]
	s_nop 0
	global_load_lds_dwordx4 v[242:243], off
	v_mfma_f32_16x16x32_bf16 v[16:19], v[168:171], v[230:233], v[16:19]
	v_lshl_add_u64 v[242:243], v[140:141], 0, s[14:15]
	s_add_i32 m0, s84, 0x2000
	v_mfma_f32_16x16x32_bf16 v[12:15], v[178:181], v[230:233], v[12:15]
	s_nop 0
	global_load_lds_dwordx4 v[242:243], off
	v_mfma_f32_16x16x32_bf16 v[64:67], v[174:177], v[218:221], v[64:67]
	v_mfma_f32_16x16x32_bf16 v[60:63], v[182:185], v[218:221], v[60:63]
	v_mfma_f32_16x16x32_bf16 v[48:51], v[174:177], v[222:225], v[48:51]
	v_mfma_f32_16x16x32_bf16 v[44:47], v[182:185], v[222:225], v[44:47]
	v_mfma_f32_16x16x32_bf16 v[32:35], v[174:177], v[234:237], v[32:35]
	v_mfma_f32_16x16x32_bf16 v[28:31], v[182:185], v[234:237], v[28:31]
	v_mfma_f32_16x16x32_bf16 v[16:19], v[174:177], v[238:241], v[16:19]
	v_mfma_f32_16x16x32_bf16 v[12:15], v[182:185], v[238:241], v[12:15]
	v_mfma_f32_16x16x32_bf16 v[56:59], v[194:197], v[210:213], v[56:59]
	v_mfma_f32_16x16x32_bf16 v[52:55], v[202:205], v[210:213], v[52:55]
	v_mfma_f32_16x16x32_bf16 v[40:43], v[194:197], v[214:217], v[40:43]
	v_mfma_f32_16x16x32_bf16 v[36:39], v[202:205], v[214:217], v[36:39]
	v_mfma_f32_16x16x32_bf16 v[24:27], v[194:197], v[226:229], v[24:27]
	v_mfma_f32_16x16x32_bf16 v[20:23], v[202:205], v[226:229], v[20:23]
	v_mfma_f32_16x16x32_bf16 v[8:11], v[194:197], v[230:233], v[8:11]
	v_mfma_f32_16x16x32_bf16 v[4:7], v[202:205], v[230:233], v[4:7]
	v_mfma_f32_16x16x32_bf16 v[56:59], v[198:201], v[218:221], v[56:59]
	v_mfma_f32_16x16x32_bf16 v[52:55], v[206:209], v[218:221], v[52:55]
	v_mfma_f32_16x16x32_bf16 v[40:43], v[198:201], v[222:225], v[40:43]
	v_mfma_f32_16x16x32_bf16 v[36:39], v[206:209], v[222:225], v[36:39]
	v_mfma_f32_16x16x32_bf16 v[24:27], v[198:201], v[234:237], v[24:27]
	v_mfma_f32_16x16x32_bf16 v[20:23], v[206:209], v[234:237], v[20:23]
	v_mfma_f32_16x16x32_bf16 v[8:11], v[198:201], v[238:241], v[8:11]
	v_mfma_f32_16x16x32_bf16 v[4:7], v[206:209], v[238:241], v[4:7]
	s_barrier
	ds_read_b128 v[168:171], v163
	ds_read_b128 v[174:177], v164
	ds_read_b128 v[178:181], v155
	ds_read_b128 v[182:185], v160
	ds_read_b128 v[194:197], v165
	ds_read_b128 v[198:201], v166
	ds_read_b128 v[202:205], v161
	ds_read_b128 v[206:209], v162
	ds_read_b128 v[210:213], v153 offset:32768
	ds_read_b128 v[214:217], v153 offset:34816
	ds_read_b128 v[218:221], v154 offset:32768
	ds_read_b128 v[222:225], v154 offset:34816
	ds_read_b128 v[226:229], v153 offset:36864
	ds_read_b128 v[230:233], v153 offset:38912
	ds_read_b128 v[234:237], v154 offset:36864
	ds_read_b128 v[238:241], v154 offset:38912
	s_waitcnt vmcnt(4)
	s_waitcnt lgkmcnt(0)
	s_barrier
	v_mfma_f32_16x16x32_bf16 v[128:131], v[168:171], v[210:213], v[128:131]
	s_mov_b32 m0, s34
	v_lshl_add_u64 v[242:243], s[70:71], 0, v[0:1]
	v_mfma_f32_16x16x32_bf16 v[124:127], v[178:181], v[210:213], v[124:127]
	global_load_lds_dwordx4 v[242:243], off
	v_lshl_add_u64 v[244:245], v[242:243], 0, s[16:17]
	v_mfma_f32_16x16x32_bf16 v[112:115], v[168:171], v[214:217], v[112:115]
	s_mov_b32 m0, s35
	s_nop 0
	v_mfma_f32_16x16x32_bf16 v[108:111], v[178:181], v[214:217], v[108:111]
	global_load_lds_dwordx4 v[244:245], off
	v_lshl_add_u64 v[244:245], v[242:243], 0, s[0:1]
	v_mfma_f32_16x16x32_bf16 v[96:99], v[168:171], v[226:229], v[96:99]
	s_mov_b32 m0, s38
	v_lshl_add_u64 v[242:243], v[242:243], 0, s[18:19]
	v_mfma_f32_16x16x32_bf16 v[92:95], v[178:181], v[226:229], v[92:95]
	global_load_lds_dwordx4 v[244:245], off
	s_mov_b32 m0, s39
	v_mfma_f32_16x16x32_bf16 v[80:83], v[168:171], v[230:233], v[80:83]
	s_nop 0
	global_load_lds_dwordx4 v[242:243], off
	v_mfma_f32_16x16x32_bf16 v[76:79], v[178:181], v[230:233], v[76:79]
	v_mfma_f32_16x16x32_bf16 v[128:131], v[174:177], v[218:221], v[128:131]
	v_mfma_f32_16x16x32_bf16 v[124:127], v[182:185], v[218:221], v[124:127]
	v_mfma_f32_16x16x32_bf16 v[112:115], v[174:177], v[222:225], v[112:115]
	v_mfma_f32_16x16x32_bf16 v[108:111], v[182:185], v[222:225], v[108:111]
	v_mfma_f32_16x16x32_bf16 v[96:99], v[174:177], v[234:237], v[96:99]
	v_mfma_f32_16x16x32_bf16 v[92:95], v[182:185], v[234:237], v[92:95]
	v_mfma_f32_16x16x32_bf16 v[80:83], v[174:177], v[238:241], v[80:83]
	v_mfma_f32_16x16x32_bf16 v[76:79], v[182:185], v[238:241], v[76:79]
	v_mfma_f32_16x16x32_bf16 v[120:123], v[194:197], v[210:213], v[120:123]
	v_mfma_f32_16x16x32_bf16 v[116:119], v[202:205], v[210:213], v[116:119]
	v_mfma_f32_16x16x32_bf16 v[104:107], v[194:197], v[214:217], v[104:107]
	v_mfma_f32_16x16x32_bf16 v[100:103], v[202:205], v[214:217], v[100:103]
	v_mfma_f32_16x16x32_bf16 v[88:91], v[194:197], v[226:229], v[88:91]
	v_mfma_f32_16x16x32_bf16 v[84:87], v[202:205], v[226:229], v[84:87]
	v_mfma_f32_16x16x32_bf16 v[72:75], v[194:197], v[230:233], v[72:75]
	v_mfma_f32_16x16x32_bf16 v[68:71], v[202:205], v[230:233], v[68:71]
	v_mfma_f32_16x16x32_bf16 v[120:123], v[198:201], v[218:221], v[120:123]
	v_mfma_f32_16x16x32_bf16 v[116:119], v[206:209], v[218:221], v[116:119]
	v_mfma_f32_16x16x32_bf16 v[104:107], v[198:201], v[222:225], v[104:107]
	v_mfma_f32_16x16x32_bf16 v[100:103], v[206:209], v[222:225], v[100:103]
	v_mfma_f32_16x16x32_bf16 v[88:91], v[198:201], v[234:237], v[88:91]
	v_mfma_f32_16x16x32_bf16 v[84:87], v[206:209], v[234:237], v[84:87]
	v_mfma_f32_16x16x32_bf16 v[72:75], v[198:201], v[238:241], v[72:75]
	v_mfma_f32_16x16x32_bf16 v[68:71], v[206:209], v[238:241], v[68:71]
	s_barrier
	ds_read_b128 v[210:213], v153 offset:49152
	ds_read_b128 v[214:217], v153 offset:51200
	ds_read_b128 v[218:221], v154 offset:49152
	ds_read_b128 v[222:225], v154 offset:51200
	ds_read_b128 v[226:229], v153 offset:53248
	ds_read_b128 v[230:233], v153 offset:55296
	ds_read_b128 v[234:237], v154 offset:53248
	ds_read_b128 v[238:241], v154 offset:55296
	s_waitcnt vmcnt(0)
	s_waitcnt lgkmcnt(0)
	s_barrier
	v_mfma_f32_16x16x32_bf16 v[64:67], v[168:171], v[210:213], v[64:67]
	s_add_i32 s70, s73, s3
	v_lshl_add_u64 v[242:243], v[140:141], 0, s[22:23]
	v_mfma_f32_16x16x32_bf16 v[60:63], v[178:181], v[210:213], v[60:63]
	s_mov_b32 m0, s70
	global_load_lds_dwordx4 v[242:243], off
	v_mfma_f32_16x16x32_bf16 v[48:51], v[168:171], v[214:217], v[48:51]
	v_lshl_add_u64 v[242:243], v[140:141], 0, s[24:25]
	s_add_i32 m0, s70, 0x2000
	v_mfma_f32_16x16x32_bf16 v[44:47], v[178:181], v[214:217], v[44:47]
	s_add_i32 s70, s77, s3
	global_load_lds_dwordx4 v[242:243], off
	v_mfma_f32_16x16x32_bf16 v[32:35], v[168:171], v[226:229], v[32:35]
	v_lshl_add_u64 v[242:243], v[140:141], 0, s[28:29]
	s_mov_b32 m0, s70
	v_mfma_f32_16x16x32_bf16 v[28:31], v[178:181], v[226:229], v[28:31]
	v_lshl_add_u64 v[140:141], v[140:141], 0, s[36:37]
	global_load_lds_dwordx4 v[242:243], off
	v_mfma_f32_16x16x32_bf16 v[16:19], v[168:171], v[230:233], v[16:19]
	s_add_i32 m0, s70, 0x2000
	s_nop 0
	v_mfma_f32_16x16x32_bf16 v[12:15], v[178:181], v[230:233], v[12:15]
	global_load_lds_dwordx4 v[140:141], off
	v_mfma_f32_16x16x32_bf16 v[64:67], v[174:177], v[218:221], v[64:67]
	v_mfma_f32_16x16x32_bf16 v[60:63], v[182:185], v[218:221], v[60:63]
	v_mfma_f32_16x16x32_bf16 v[48:51], v[174:177], v[222:225], v[48:51]
	v_mfma_f32_16x16x32_bf16 v[44:47], v[182:185], v[222:225], v[44:47]
	v_mfma_f32_16x16x32_bf16 v[32:35], v[174:177], v[234:237], v[32:35]
	v_mfma_f32_16x16x32_bf16 v[28:31], v[182:185], v[234:237], v[28:31]
	v_mfma_f32_16x16x32_bf16 v[16:19], v[174:177], v[238:241], v[16:19]
	v_mfma_f32_16x16x32_bf16 v[12:15], v[182:185], v[238:241], v[12:15]
	v_mfma_f32_16x16x32_bf16 v[56:59], v[194:197], v[210:213], v[56:59]
	v_mfma_f32_16x16x32_bf16 v[52:55], v[202:205], v[210:213], v[52:55]
	v_mfma_f32_16x16x32_bf16 v[40:43], v[194:197], v[214:217], v[40:43]
	v_mfma_f32_16x16x32_bf16 v[36:39], v[202:205], v[214:217], v[36:39]
	v_mfma_f32_16x16x32_bf16 v[24:27], v[194:197], v[226:229], v[24:27]
	v_mfma_f32_16x16x32_bf16 v[20:23], v[202:205], v[226:229], v[20:23]
	v_mfma_f32_16x16x32_bf16 v[8:11], v[194:197], v[230:233], v[8:11]
	v_mfma_f32_16x16x32_bf16 v[4:7], v[202:205], v[230:233], v[4:7]
	v_mfma_f32_16x16x32_bf16 v[56:59], v[198:201], v[218:221], v[56:59]
	v_mfma_f32_16x16x32_bf16 v[52:55], v[206:209], v[218:221], v[52:55]
	v_mfma_f32_16x16x32_bf16 v[40:43], v[198:201], v[222:225], v[40:43]
	v_mfma_f32_16x16x32_bf16 v[36:39], v[206:209], v[222:225], v[36:39]
	v_mfma_f32_16x16x32_bf16 v[24:27], v[198:201], v[234:237], v[24:27]
	v_mfma_f32_16x16x32_bf16 v[20:23], v[206:209], v[234:237], v[20:23]
	v_mfma_f32_16x16x32_bf16 v[8:11], v[198:201], v[238:241], v[8:11]
	v_mfma_f32_16x16x32_bf16 v[4:7], v[206:209], v[238:241], v[4:7]
	s_barrier
	s_add_i32 s83, s83, 2
	s_add_u32 s68, s68, 0x100
	s_addc_u32 s69, s69, 0
	s_cmp_gt_u32 s83, 13
	s_cbranch_scc0 .LBB0_1135
	s_and_b64 vcc, exec, s[40:41]
	s_cbranch_vccz .LBB0_1138
	s_barrier
